# P6 FFN gate/up epilogue rewritten by hand: dpp-add row sums, plain rsq, pack-then-perm paired stores, 32-bit store offsets (1350 -> 914 instr per wave-tile); same math
# speedup vs baseline: 1.0143x; 1.0143x over previous
; __device__ __forceinline__ float row16_sum(float v) {
;   v += dpp_f<0x128>(v); v += dpp_f<0x124>(v); v += dpp_f<0x122>(v); v += dpp_f<0x121>(v);
;   return v;
; }
;   __device__ __forceinline__ void operator()(f32x4 (&acc)[2][2][4][2], int brow, int bcol, int wr, int wc, int fr, int fq) const {
;     ...
;     float sv[2][4][4];
; #pragma unroll
;     for (int ai = 0; ai < 2; ++ai)
; #pragma unroll
;       for (int m = 0; m < 4; ++m)
; #pragma unroll
;         for (int j = 0; j < 4; ++j) sv[ai][m][j] = ssq1[(size_t)(brow + ai * 128 + wr * 64 + m * 16 + fq * 4 + j) * 16 + fr];
;     __builtin_amdgcn_sched_barrier(0);
; #pragma unroll
;     for (int ai = 0; ai < 2; ++ai)
; #pragma unroll
;       for (int m = 0; m < 4; ++m) {
;         int row0 = brow + ai * 128 + wr * 64 + m * 16 + fq * 4;
;         float rs[4];
; #pragma unroll
;         for (int j = 0; j < 4; ++j) rs[j] = rsqrtf(row16_sum(sv[ai][m][j]) * (1.f / 1024.f) + 1e-6f);
.LBB0_579:
	v_mbcnt_lo_u32_b32 v163, -1, 0
	v_mbcnt_hi_u32_b32 v163, -1, v163
	s_lshl_b32 s3, s2, 6
	s_add_u32 s98, s8, s3
	s_addc_u32 s99, s9, 0
	s_add_u32 s100, s98, 0x2000
	s_addc_u32 s101, s99, 0
	s_lshr_b32 s3, s33, 8
	s_lshl_b32 s4, s3, 12
	v_and_b32_e32 v128, 15, v163
	v_lshrrev_b32_e32 v167, 4, v163
	v_and_b32_e32 v168, 1, v163
	v_lshlrev_b32_e32 v128, 2, v128
	v_lshl_add_u32 v128, v167, 8, v128
	v_add_u32_e32 v128, s4, v128
	global_load_dword v130, v128, s[98:99] offset:0
	global_load_dword v131, v128, s[98:99] offset:64
	global_load_dword v132, v128, s[98:99] offset:128
	global_load_dword v133, v128, s[98:99] offset:192
	global_load_dword v134, v128, s[98:99] offset:1024
	global_load_dword v135, v128, s[98:99] offset:1088
	global_load_dword v136, v128, s[98:99] offset:1152
	global_load_dword v137, v128, s[98:99] offset:1216
	global_load_dword v138, v128, s[98:99] offset:2048
	global_load_dword v139, v128, s[98:99] offset:2112
	global_load_dword v140, v128, s[98:99] offset:2176
	global_load_dword v141, v128, s[98:99] offset:2240
	global_load_dword v142, v128, s[98:99] offset:3072
	global_load_dword v143, v128, s[98:99] offset:3136
	global_load_dword v144, v128, s[98:99] offset:3200
	global_load_dword v145, v128, s[98:99] offset:3264
	global_load_dword v146, v128, s[100:101] offset:0
	global_load_dword v147, v128, s[100:101] offset:64
	global_load_dword v148, v128, s[100:101] offset:128
	global_load_dword v149, v128, s[100:101] offset:192
	global_load_dword v150, v128, s[100:101] offset:1024
	global_load_dword v151, v128, s[100:101] offset:1088
	global_load_dword v152, v128, s[100:101] offset:1152
	global_load_dword v153, v128, s[100:101] offset:1216
	global_load_dword v154, v128, s[100:101] offset:2048
	global_load_dword v155, v128, s[100:101] offset:2112
	global_load_dword v156, v128, s[100:101] offset:2176
	global_load_dword v157, v128, s[100:101] offset:2240
	global_load_dword v158, v128, s[100:101] offset:3072
	global_load_dword v159, v128, s[100:101] offset:3136
	global_load_dword v160, v128, s[100:101] offset:3200
	global_load_dword v161, v128, s[100:101] offset:3264
	s_ashr_i32 s0, s0, 1
	s_and_b32 s0, s0, 0xffffff80
	s_bfe_u32 s4, s33, 0x20006
	s_lshl_b32 s4, s4, 5
	s_add_i32 s0, s0, s4
	s_lshl_b32 s3, s3, 6
	s_add_i32 s3, s3, s2
	v_lshl_add_u32 v166, v167, 2, v168
	v_add_u32_e32 v166, s3, v166
	v_mul_u32_u24_e32 v166, 0x1600, v166
	v_and_b32_e32 v172, 14, v163
	v_add_u32_e32 v172, s0, v172
	v_lshl_add_u32 v166, v172, 1, v166
	v_mov_b32_e32 v164, 0x05040100
	v_mov_b32_e32 v173, 0x03020706
	v_cmp_eq_u32_e32 vcc, 1, v168
	v_mov_b32_e32 v165, 0x358637bd
	v_cndmask_b32_e32 v164, v164, v173, vcc
	s_waitcnt vmcnt(0)
	v_add_f32_dpp v130, v130, v130 row_ror:8 row_mask:0xf bank_mask:0xf bound_ctrl:1
	v_add_f32_dpp v131, v131, v131 row_ror:8 row_mask:0xf bank_mask:0xf bound_ctrl:1
	v_add_f32_dpp v132, v132, v132 row_ror:8 row_mask:0xf bank_mask:0xf bound_ctrl:1
	v_add_f32_dpp v133, v133, v133 row_ror:8 row_mask:0xf bank_mask:0xf bound_ctrl:1
	v_add_f32_dpp v134, v134, v134 row_ror:8 row_mask:0xf bank_mask:0xf bound_ctrl:1
	v_add_f32_dpp v135, v135, v135 row_ror:8 row_mask:0xf bank_mask:0xf bound_ctrl:1
	v_add_f32_dpp v136, v136, v136 row_ror:8 row_mask:0xf bank_mask:0xf bound_ctrl:1
	v_add_f32_dpp v137, v137, v137 row_ror:8 row_mask:0xf bank_mask:0xf bound_ctrl:1
	v_add_f32_dpp v138, v138, v138 row_ror:8 row_mask:0xf bank_mask:0xf bound_ctrl:1
	v_add_f32_dpp v139, v139, v139 row_ror:8 row_mask:0xf bank_mask:0xf bound_ctrl:1
	v_add_f32_dpp v140, v140, v140 row_ror:8 row_mask:0xf bank_mask:0xf bound_ctrl:1
	v_add_f32_dpp v141, v141, v141 row_ror:8 row_mask:0xf bank_mask:0xf bound_ctrl:1
	v_add_f32_dpp v142, v142, v142 row_ror:8 row_mask:0xf bank_mask:0xf bound_ctrl:1
	v_add_f32_dpp v143, v143, v143 row_ror:8 row_mask:0xf bank_mask:0xf bound_ctrl:1
	v_add_f32_dpp v144, v144, v144 row_ror:8 row_mask:0xf bank_mask:0xf bound_ctrl:1
	v_add_f32_dpp v145, v145, v145 row_ror:8 row_mask:0xf bank_mask:0xf bound_ctrl:1
	v_add_f32_dpp v146, v146, v146 row_ror:8 row_mask:0xf bank_mask:0xf bound_ctrl:1
	v_add_f32_dpp v147, v147, v147 row_ror:8 row_mask:0xf bank_mask:0xf bound_ctrl:1
	v_add_f32_dpp v148, v148, v148 row_ror:8 row_mask:0xf bank_mask:0xf bound_ctrl:1
	v_add_f32_dpp v149, v149, v149 row_ror:8 row_mask:0xf bank_mask:0xf bound_ctrl:1
	v_add_f32_dpp v150, v150, v150 row_ror:8 row_mask:0xf bank_mask:0xf bound_ctrl:1
	v_add_f32_dpp v151, v151, v151 row_ror:8 row_mask:0xf bank_mask:0xf bound_ctrl:1
	v_add_f32_dpp v152, v152, v152 row_ror:8 row_mask:0xf bank_mask:0xf bound_ctrl:1
	v_add_f32_dpp v153, v153, v153 row_ror:8 row_mask:0xf bank_mask:0xf bound_ctrl:1
	v_add_f32_dpp v154, v154, v154 row_ror:8 row_mask:0xf bank_mask:0xf bound_ctrl:1
	v_add_f32_dpp v155, v155, v155 row_ror:8 row_mask:0xf bank_mask:0xf bound_ctrl:1
	v_add_f32_dpp v156, v156, v156 row_ror:8 row_mask:0xf bank_mask:0xf bound_ctrl:1
	v_add_f32_dpp v157, v157, v157 row_ror:8 row_mask:0xf bank_mask:0xf bound_ctrl:1
	v_add_f32_dpp v158, v158, v158 row_ror:8 row_mask:0xf bank_mask:0xf bound_ctrl:1
	v_add_f32_dpp v159, v159, v159 row_ror:8 row_mask:0xf bank_mask:0xf bound_ctrl:1
	v_add_f32_dpp v160, v160, v160 row_ror:8 row_mask:0xf bank_mask:0xf bound_ctrl:1
	v_add_f32_dpp v161, v161, v161 row_ror:8 row_mask:0xf bank_mask:0xf bound_ctrl:1
	v_add_f32_dpp v130, v130, v130 row_ror:4 row_mask:0xf bank_mask:0xf bound_ctrl:1
	v_add_f32_dpp v131, v131, v131 row_ror:4 row_mask:0xf bank_mask:0xf bound_ctrl:1
	v_add_f32_dpp v132, v132, v132 row_ror:4 row_mask:0xf bank_mask:0xf bound_ctrl:1
	v_add_f32_dpp v133, v133, v133 row_ror:4 row_mask:0xf bank_mask:0xf bound_ctrl:1
; __device__ __forceinline__ float row16_sum(float v) {
;   v += dpp_f<0x128>(v); v += dpp_f<0x124>(v); v += dpp_f<0x122>(v); v += dpp_f<0x121>(v);
;   return v;
; }
;   __device__ __forceinline__ void operator()(f32x4 (&acc)[2][2][4][2], int brow, int bcol, int wr, int wc, int fr, int fq) const {
;     ...
;         for (int j = 0; j < 4; ++j) rs[j] = rsqrtf(row16_sum(sv[ai][m][j]) * (1.f / 1024.f) + 1e-6f);
	v_add_f32_dpp v134, v134, v134 row_ror:4 row_mask:0xf bank_mask:0xf bound_ctrl:1
	v_add_f32_dpp v135, v135, v135 row_ror:4 row_mask:0xf bank_mask:0xf bound_ctrl:1
	v_add_f32_dpp v136, v136, v136 row_ror:4 row_mask:0xf bank_mask:0xf bound_ctrl:1
	v_add_f32_dpp v137, v137, v137 row_ror:4 row_mask:0xf bank_mask:0xf bound_ctrl:1
	v_add_f32_dpp v138, v138, v138 row_ror:4 row_mask:0xf bank_mask:0xf bound_ctrl:1
	v_add_f32_dpp v139, v139, v139 row_ror:4 row_mask:0xf bank_mask:0xf bound_ctrl:1
	v_add_f32_dpp v140, v140, v140 row_ror:4 row_mask:0xf bank_mask:0xf bound_ctrl:1
	v_add_f32_dpp v141, v141, v141 row_ror:4 row_mask:0xf bank_mask:0xf bound_ctrl:1
	v_add_f32_dpp v142, v142, v142 row_ror:4 row_mask:0xf bank_mask:0xf bound_ctrl:1
	v_add_f32_dpp v143, v143, v143 row_ror:4 row_mask:0xf bank_mask:0xf bound_ctrl:1
	v_add_f32_dpp v144, v144, v144 row_ror:4 row_mask:0xf bank_mask:0xf bound_ctrl:1
	v_add_f32_dpp v145, v145, v145 row_ror:4 row_mask:0xf bank_mask:0xf bound_ctrl:1
	v_add_f32_dpp v146, v146, v146 row_ror:4 row_mask:0xf bank_mask:0xf bound_ctrl:1
	v_add_f32_dpp v147, v147, v147 row_ror:4 row_mask:0xf bank_mask:0xf bound_ctrl:1
	v_add_f32_dpp v148, v148, v148 row_ror:4 row_mask:0xf bank_mask:0xf bound_ctrl:1
	v_add_f32_dpp v149, v149, v149 row_ror:4 row_mask:0xf bank_mask:0xf bound_ctrl:1
	v_add_f32_dpp v150, v150, v150 row_ror:4 row_mask:0xf bank_mask:0xf bound_ctrl:1
	v_add_f32_dpp v151, v151, v151 row_ror:4 row_mask:0xf bank_mask:0xf bound_ctrl:1
	v_add_f32_dpp v152, v152, v152 row_ror:4 row_mask:0xf bank_mask:0xf bound_ctrl:1
	v_add_f32_dpp v153, v153, v153 row_ror:4 row_mask:0xf bank_mask:0xf bound_ctrl:1
	v_add_f32_dpp v154, v154, v154 row_ror:4 row_mask:0xf bank_mask:0xf bound_ctrl:1
	v_add_f32_dpp v155, v155, v155 row_ror:4 row_mask:0xf bank_mask:0xf bound_ctrl:1
	v_add_f32_dpp v156, v156, v156 row_ror:4 row_mask:0xf bank_mask:0xf bound_ctrl:1
	v_add_f32_dpp v157, v157, v157 row_ror:4 row_mask:0xf bank_mask:0xf bound_ctrl:1
	v_add_f32_dpp v158, v158, v158 row_ror:4 row_mask:0xf bank_mask:0xf bound_ctrl:1
	v_add_f32_dpp v159, v159, v159 row_ror:4 row_mask:0xf bank_mask:0xf bound_ctrl:1
	v_add_f32_dpp v160, v160, v160 row_ror:4 row_mask:0xf bank_mask:0xf bound_ctrl:1
	v_add_f32_dpp v161, v161, v161 row_ror:4 row_mask:0xf bank_mask:0xf bound_ctrl:1
	v_add_f32_dpp v130, v130, v130 row_ror:2 row_mask:0xf bank_mask:0xf bound_ctrl:1
	v_add_f32_dpp v131, v131, v131 row_ror:2 row_mask:0xf bank_mask:0xf bound_ctrl:1
	v_add_f32_dpp v132, v132, v132 row_ror:2 row_mask:0xf bank_mask:0xf bound_ctrl:1
	v_add_f32_dpp v133, v133, v133 row_ror:2 row_mask:0xf bank_mask:0xf bound_ctrl:1
	v_add_f32_dpp v134, v134, v134 row_ror:2 row_mask:0xf bank_mask:0xf bound_ctrl:1
	v_add_f32_dpp v135, v135, v135 row_ror:2 row_mask:0xf bank_mask:0xf bound_ctrl:1
	v_add_f32_dpp v136, v136, v136 row_ror:2 row_mask:0xf bank_mask:0xf bound_ctrl:1
	v_add_f32_dpp v137, v137, v137 row_ror:2 row_mask:0xf bank_mask:0xf bound_ctrl:1
	v_add_f32_dpp v138, v138, v138 row_ror:2 row_mask:0xf bank_mask:0xf bound_ctrl:1
	v_add_f32_dpp v139, v139, v139 row_ror:2 row_mask:0xf bank_mask:0xf bound_ctrl:1
	v_add_f32_dpp v140, v140, v140 row_ror:2 row_mask:0xf bank_mask:0xf bound_ctrl:1
	v_add_f32_dpp v141, v141, v141 row_ror:2 row_mask:0xf bank_mask:0xf bound_ctrl:1
	v_add_f32_dpp v142, v142, v142 row_ror:2 row_mask:0xf bank_mask:0xf bound_ctrl:1
	v_add_f32_dpp v143, v143, v143 row_ror:2 row_mask:0xf bank_mask:0xf bound_ctrl:1
	v_add_f32_dpp v144, v144, v144 row_ror:2 row_mask:0xf bank_mask:0xf bound_ctrl:1
	v_add_f32_dpp v145, v145, v145 row_ror:2 row_mask:0xf bank_mask:0xf bound_ctrl:1
	v_add_f32_dpp v146, v146, v146 row_ror:2 row_mask:0xf bank_mask:0xf bound_ctrl:1
	v_add_f32_dpp v147, v147, v147 row_ror:2 row_mask:0xf bank_mask:0xf bound_ctrl:1
	v_add_f32_dpp v148, v148, v148 row_ror:2 row_mask:0xf bank_mask:0xf bound_ctrl:1
	v_add_f32_dpp v149, v149, v149 row_ror:2 row_mask:0xf bank_mask:0xf bound_ctrl:1
	v_add_f32_dpp v150, v150, v150 row_ror:2 row_mask:0xf bank_mask:0xf bound_ctrl:1
	v_add_f32_dpp v151, v151, v151 row_ror:2 row_mask:0xf bank_mask:0xf bound_ctrl:1
	v_add_f32_dpp v152, v152, v152 row_ror:2 row_mask:0xf bank_mask:0xf bound_ctrl:1
	v_add_f32_dpp v153, v153, v153 row_ror:2 row_mask:0xf bank_mask:0xf bound_ctrl:1
	v_add_f32_dpp v154, v154, v154 row_ror:2 row_mask:0xf bank_mask:0xf bound_ctrl:1
	v_add_f32_dpp v155, v155, v155 row_ror:2 row_mask:0xf bank_mask:0xf bound_ctrl:1
	v_add_f32_dpp v156, v156, v156 row_ror:2 row_mask:0xf bank_mask:0xf bound_ctrl:1
	v_add_f32_dpp v157, v157, v157 row_ror:2 row_mask:0xf bank_mask:0xf bound_ctrl:1
	v_add_f32_dpp v158, v158, v158 row_ror:2 row_mask:0xf bank_mask:0xf bound_ctrl:1
	v_add_f32_dpp v159, v159, v159 row_ror:2 row_mask:0xf bank_mask:0xf bound_ctrl:1
	v_add_f32_dpp v160, v160, v160 row_ror:2 row_mask:0xf bank_mask:0xf bound_ctrl:1
	v_add_f32_dpp v161, v161, v161 row_ror:2 row_mask:0xf bank_mask:0xf bound_ctrl:1
	v_add_f32_dpp v130, v130, v130 row_ror:1 row_mask:0xf bank_mask:0xf bound_ctrl:1
	v_add_f32_dpp v131, v131, v131 row_ror:1 row_mask:0xf bank_mask:0xf bound_ctrl:1
	v_add_f32_dpp v132, v132, v132 row_ror:1 row_mask:0xf bank_mask:0xf bound_ctrl:1
	v_add_f32_dpp v133, v133, v133 row_ror:1 row_mask:0xf bank_mask:0xf bound_ctrl:1
	v_add_f32_dpp v134, v134, v134 row_ror:1 row_mask:0xf bank_mask:0xf bound_ctrl:1
	v_add_f32_dpp v135, v135, v135 row_ror:1 row_mask:0xf bank_mask:0xf bound_ctrl:1
	v_add_f32_dpp v136, v136, v136 row_ror:1 row_mask:0xf bank_mask:0xf bound_ctrl:1
	v_add_f32_dpp v137, v137, v137 row_ror:1 row_mask:0xf bank_mask:0xf bound_ctrl:1
	v_add_f32_dpp v138, v138, v138 row_ror:1 row_mask:0xf bank_mask:0xf bound_ctrl:1
; __device__ __forceinline__ float fast_silu(float z) { return z * __builtin_amdgcn_rcpf(1.f + __expf(-z)); }
;   __device__ __forceinline__ void operator()(f32x4 (&acc)[2][2][4][2], int brow, int bcol, int wr, int wc, int fr, int fq) const {
;     ...
;         float rs[4];
; #pragma unroll
;         for (int j = 0; j < 4; ++j) rs[j] = rsqrtf(row16_sum(sv[ai][m][j]) * (1.f / 1024.f) + 1e-6f);
; #pragma unroll
;         for (int n = 0; n < 2; ++n) {
;           float a[4];
; #pragma unroll
;           for (int j = 0; j < 4; ++j) {
;             float g = acc[ai][0][m][n][j] * rs[j], u = acc[ai][1][m][n][j] * rs[j];
;             a[j] = fast_silu(g) * u;
	v_add_f32_dpp v139, v139, v139 row_ror:1 row_mask:0xf bank_mask:0xf bound_ctrl:1
	v_add_f32_dpp v140, v140, v140 row_ror:1 row_mask:0xf bank_mask:0xf bound_ctrl:1
	v_add_f32_dpp v141, v141, v141 row_ror:1 row_mask:0xf bank_mask:0xf bound_ctrl:1
	v_add_f32_dpp v142, v142, v142 row_ror:1 row_mask:0xf bank_mask:0xf bound_ctrl:1
	v_add_f32_dpp v143, v143, v143 row_ror:1 row_mask:0xf bank_mask:0xf bound_ctrl:1
	v_add_f32_dpp v144, v144, v144 row_ror:1 row_mask:0xf bank_mask:0xf bound_ctrl:1
	v_add_f32_dpp v145, v145, v145 row_ror:1 row_mask:0xf bank_mask:0xf bound_ctrl:1
	v_add_f32_dpp v146, v146, v146 row_ror:1 row_mask:0xf bank_mask:0xf bound_ctrl:1
	v_add_f32_dpp v147, v147, v147 row_ror:1 row_mask:0xf bank_mask:0xf bound_ctrl:1
	v_add_f32_dpp v148, v148, v148 row_ror:1 row_mask:0xf bank_mask:0xf bound_ctrl:1
	v_add_f32_dpp v149, v149, v149 row_ror:1 row_mask:0xf bank_mask:0xf bound_ctrl:1
	v_add_f32_dpp v150, v150, v150 row_ror:1 row_mask:0xf bank_mask:0xf bound_ctrl:1
	v_add_f32_dpp v151, v151, v151 row_ror:1 row_mask:0xf bank_mask:0xf bound_ctrl:1
	v_add_f32_dpp v152, v152, v152 row_ror:1 row_mask:0xf bank_mask:0xf bound_ctrl:1
	v_add_f32_dpp v153, v153, v153 row_ror:1 row_mask:0xf bank_mask:0xf bound_ctrl:1
	v_add_f32_dpp v154, v154, v154 row_ror:1 row_mask:0xf bank_mask:0xf bound_ctrl:1
	v_add_f32_dpp v155, v155, v155 row_ror:1 row_mask:0xf bank_mask:0xf bound_ctrl:1
	v_add_f32_dpp v156, v156, v156 row_ror:1 row_mask:0xf bank_mask:0xf bound_ctrl:1
	v_add_f32_dpp v157, v157, v157 row_ror:1 row_mask:0xf bank_mask:0xf bound_ctrl:1
	v_add_f32_dpp v158, v158, v158 row_ror:1 row_mask:0xf bank_mask:0xf bound_ctrl:1
	v_add_f32_dpp v159, v159, v159 row_ror:1 row_mask:0xf bank_mask:0xf bound_ctrl:1
	v_add_f32_dpp v160, v160, v160 row_ror:1 row_mask:0xf bank_mask:0xf bound_ctrl:1
	v_add_f32_dpp v161, v161, v161 row_ror:1 row_mask:0xf bank_mask:0xf bound_ctrl:1
	v_fma_f32 v130, v130, s24, v165
	v_fma_f32 v131, v131, s24, v165
	v_fma_f32 v132, v132, s24, v165
	v_fma_f32 v133, v133, s24, v165
	v_fma_f32 v134, v134, s24, v165
	v_fma_f32 v135, v135, s24, v165
	v_fma_f32 v136, v136, s24, v165
	v_fma_f32 v137, v137, s24, v165
	v_fma_f32 v138, v138, s24, v165
	v_fma_f32 v139, v139, s24, v165
	v_fma_f32 v140, v140, s24, v165
	v_fma_f32 v141, v141, s24, v165
	v_fma_f32 v142, v142, s24, v165
	v_fma_f32 v143, v143, s24, v165
	v_fma_f32 v144, v144, s24, v165
	v_fma_f32 v145, v145, s24, v165
	v_fma_f32 v146, v146, s24, v165
	v_fma_f32 v147, v147, s24, v165
	v_fma_f32 v148, v148, s24, v165
	v_fma_f32 v149, v149, s24, v165
	v_fma_f32 v150, v150, s24, v165
	v_fma_f32 v151, v151, s24, v165
	v_fma_f32 v152, v152, s24, v165
	v_fma_f32 v153, v153, s24, v165
	v_fma_f32 v154, v154, s24, v165
	v_fma_f32 v155, v155, s24, v165
	v_fma_f32 v156, v156, s24, v165
	v_fma_f32 v157, v157, s24, v165
	v_fma_f32 v158, v158, s24, v165
	v_fma_f32 v159, v159, s24, v165
	v_fma_f32 v160, v160, s24, v165
	v_fma_f32 v161, v161, s24, v165
	v_rsq_f32_e32 v130, v130
	v_rsq_f32_e32 v131, v131
	v_rsq_f32_e32 v132, v132
	v_rsq_f32_e32 v133, v133
	v_rsq_f32_e32 v134, v134
	v_rsq_f32_e32 v135, v135
	v_rsq_f32_e32 v136, v136
	v_rsq_f32_e32 v137, v137
	v_rsq_f32_e32 v138, v138
	v_rsq_f32_e32 v139, v139
	v_rsq_f32_e32 v140, v140
	v_rsq_f32_e32 v141, v141
	v_rsq_f32_e32 v142, v142
	v_rsq_f32_e32 v143, v143
	v_rsq_f32_e32 v144, v144
	v_rsq_f32_e32 v145, v145
	v_rsq_f32_e32 v146, v146
	v_rsq_f32_e32 v147, v147
	v_rsq_f32_e32 v148, v148
	v_rsq_f32_e32 v149, v149
	v_rsq_f32_e32 v150, v150
	v_rsq_f32_e32 v151, v151
	v_rsq_f32_e32 v152, v152
	v_rsq_f32_e32 v153, v153
	v_rsq_f32_e32 v154, v154
	v_rsq_f32_e32 v155, v155
	v_rsq_f32_e32 v156, v156
	v_rsq_f32_e32 v157, v157
	v_rsq_f32_e32 v158, v158
	v_rsq_f32_e32 v159, v159
	v_rsq_f32_e32 v160, v160
	v_rsq_f32_e32 v161, v161
	v_mov_b32_e32 v169, v166
	v_add_u32_e32 v170, 0x2c00, v166
	v_mul_f32_e32 v120, v120, v130
	v_mul_f32_e32 v121, v121, v131
	v_mul_f32_e32 v122, v122, v132
	v_mul_f32_e32 v123, v123, v133
	v_mul_f32_e32 v112, v112, v130
	v_mul_f32_e32 v113, v113, v131
	v_mul_f32_e32 v114, v114, v132
	v_mul_f32_e32 v115, v115, v133
	v_mul_f32_e32 v124, v124, v130
	v_mul_f32_e32 v125, v125, v131
	v_mul_f32_e32 v126, v126, v132
	v_mul_f32_e32 v127, v127, v133
	v_mul_f32_e32 v116, v116, v130
	v_mul_f32_e32 v117, v117, v131
	v_mul_f32_e32 v118, v118, v132
	v_mul_f32_e32 v119, v119, v133
	v_mul_f32_e32 v172, 0xbfb8aa3b, v120
	v_mul_f32_e32 v173, 0xbfb8aa3b, v121
	v_mul_f32_e32 v174, 0xbfb8aa3b, v122
	v_mul_f32_e32 v175, 0xbfb8aa3b, v123
	v_mul_f32_e32 v176, 0xbfb8aa3b, v112
	v_mul_f32_e32 v177, 0xbfb8aa3b, v113
	v_mul_f32_e32 v178, 0xbfb8aa3b, v114
	v_mul_f32_e32 v179, 0xbfb8aa3b, v115
	v_exp_f32_e32 v172, v172
	v_exp_f32_e32 v173, v173
	v_exp_f32_e32 v174, v174
	v_exp_f32_e32 v175, v175
	v_exp_f32_e32 v176, v176
	v_exp_f32_e32 v177, v177
	v_exp_f32_e32 v178, v178
	v_exp_f32_e32 v179, v179
	v_add_f32_e32 v172, 1.0, v172
	v_add_f32_e32 v173, 1.0, v173
	v_add_f32_e32 v174, 1.0, v174
	v_add_f32_e32 v175, 1.0, v175
	v_add_f32_e32 v176, 1.0, v176
	v_add_f32_e32 v177, 1.0, v177
	v_add_f32_e32 v178, 1.0, v178
	v_add_f32_e32 v179, 1.0, v179
	v_rcp_f32_e32 v172, v172
	v_rcp_f32_e32 v173, v173
	v_rcp_f32_e32 v174, v174
	v_rcp_f32_e32 v175, v175
	v_rcp_f32_e32 v176, v176
	v_rcp_f32_e32 v177, v177
	v_rcp_f32_e32 v178, v178
	v_rcp_f32_e32 v179, v179
	v_mul_f32_e32 v172, v120, v172
	v_mul_f32_e32 v173, v121, v173
	v_mul_f32_e32 v174, v122, v174
	v_mul_f32_e32 v175, v123, v175
	v_mul_f32_e32 v176, v112, v176
	v_mul_f32_e32 v177, v113, v177
	v_mul_f32_e32 v178, v114, v178
	v_mul_f32_e32 v179, v115, v179
	v_mul_f32_e32 v120, v124, v172
	v_mul_f32_e32 v121, v125, v173
; __device__ __forceinline__ float fast_silu(float z) { return z * __builtin_amdgcn_rcpf(1.f + __expf(-z)); }
; __device__ __forceinline__ void store_rm4(u16* dst, size_t ld, int row0, int c, float v0, float v1, float v2, float v3, bool odd) {
;   {
;     float s = odd ? v0 : v1, r = dpp_swap1(s);
;     float lo = odd ? r : v0, hi = odd ? v1 : r;
;     *(unsigned*)(dst + (size_t)(row0 + (odd ? 1 : 0)) * ld + (c - (odd ? 1 : 0))) = pack2(lo, hi);
;   }
;   {
;     float s = odd ? v2 : v3, r = dpp_swap1(s);
;     float lo = odd ? r : v2, hi = odd ? v3 : r;
;     *(unsigned*)(dst + (size_t)(row0 + 2 + (odd ? 1 : 0)) * ld + (c - (odd ? 1 : 0))) = pack2(lo, hi);
;   }
; }
;   __device__ __forceinline__ void operator()(f32x4 (&acc)[2][2][4][2], int brow, int bcol, int wr, int wc, int fr, int fq) const {
;     ...
; #pragma unroll
;         for (int n = 0; n < 2; ++n) {
;           float a[4];
; #pragma unroll
;           for (int j = 0; j < 4; ++j) {
;             float g = acc[ai][0][m][n][j] * rs[j], u = acc[ai][1][m][n][j] * rs[j];
;             a[j] = fast_silu(g) * u;
;           }
;           store_rm4(act, 2816, row0, t * 128 + wc * 32 + n * 16 + fr, a[0], a[1], a[2], a[3], fr & 1);
;         }
	v_mul_f32_e32 v122, v126, v174
	v_mul_f32_e32 v123, v127, v175
	v_mul_f32_e32 v112, v116, v176
	v_mul_f32_e32 v113, v117, v177
	v_mul_f32_e32 v114, v118, v178
	v_mul_f32_e32 v115, v119, v179
	v_cvt_pk_bf16_f32 v180, v120, v121
	v_cvt_pk_bf16_f32 v181, v122, v123
	v_cvt_pk_bf16_f32 v182, v112, v113
	v_cvt_pk_bf16_f32 v183, v114, v115
	v_mov_b32_dpp v184, v180 quad_perm:[1,0,3,2] row_mask:0xf bank_mask:0xf bound_ctrl:1
	v_mov_b32_dpp v185, v181 quad_perm:[1,0,3,2] row_mask:0xf bank_mask:0xf bound_ctrl:1
	v_mov_b32_dpp v186, v182 quad_perm:[1,0,3,2] row_mask:0xf bank_mask:0xf bound_ctrl:1
	v_mov_b32_dpp v187, v183 quad_perm:[1,0,3,2] row_mask:0xf bank_mask:0xf bound_ctrl:1
	v_perm_b32 v180, v184, v180, v164
	v_perm_b32 v181, v185, v181, v164
	v_perm_b32 v182, v186, v182, v164
	v_perm_b32 v183, v187, v183, v164
	global_store_dword v169, v180, s[34:35]
	global_store_dword v170, v181, s[34:35]
	global_store_dword v169, v182, s[34:35] offset:32
	global_store_dword v170, v183, s[34:35] offset:32
	v_add_u32_e32 v169, 0x16000, v166
	v_add_u32_e32 v170, 0x18c00, v166
	v_mul_f32_e32 v104, v104, v134
	v_mul_f32_e32 v105, v105, v135
	v_mul_f32_e32 v106, v106, v136
	v_mul_f32_e32 v107, v107, v137
	v_mul_f32_e32 v96, v96, v134
	v_mul_f32_e32 v97, v97, v135
	v_mul_f32_e32 v98, v98, v136
	v_mul_f32_e32 v99, v99, v137
	v_mul_f32_e32 v108, v108, v134
	v_mul_f32_e32 v109, v109, v135
	v_mul_f32_e32 v110, v110, v136
	v_mul_f32_e32 v111, v111, v137
	v_mul_f32_e32 v100, v100, v134
	v_mul_f32_e32 v101, v101, v135
	v_mul_f32_e32 v102, v102, v136
	v_mul_f32_e32 v103, v103, v137
	v_mul_f32_e32 v172, 0xbfb8aa3b, v104
	v_mul_f32_e32 v173, 0xbfb8aa3b, v105
	v_mul_f32_e32 v174, 0xbfb8aa3b, v106
	v_mul_f32_e32 v175, 0xbfb8aa3b, v107
	v_mul_f32_e32 v176, 0xbfb8aa3b, v96
	v_mul_f32_e32 v177, 0xbfb8aa3b, v97
	v_mul_f32_e32 v178, 0xbfb8aa3b, v98
	v_mul_f32_e32 v179, 0xbfb8aa3b, v99
	v_exp_f32_e32 v172, v172
	v_exp_f32_e32 v173, v173
	v_exp_f32_e32 v174, v174
	v_exp_f32_e32 v175, v175
	v_exp_f32_e32 v176, v176
	v_exp_f32_e32 v177, v177
	v_exp_f32_e32 v178, v178
	v_exp_f32_e32 v179, v179
	v_add_f32_e32 v172, 1.0, v172
	v_add_f32_e32 v173, 1.0, v173
	v_add_f32_e32 v174, 1.0, v174
	v_add_f32_e32 v175, 1.0, v175
	v_add_f32_e32 v176, 1.0, v176
	v_add_f32_e32 v177, 1.0, v177
	v_add_f32_e32 v178, 1.0, v178
	v_add_f32_e32 v179, 1.0, v179
	v_rcp_f32_e32 v172, v172
	v_rcp_f32_e32 v173, v173
	v_rcp_f32_e32 v174, v174
	v_rcp_f32_e32 v175, v175
	v_rcp_f32_e32 v176, v176
	v_rcp_f32_e32 v177, v177
	v_rcp_f32_e32 v178, v178
	v_rcp_f32_e32 v179, v179
	v_mul_f32_e32 v172, v104, v172
	v_mul_f32_e32 v173, v105, v173
	v_mul_f32_e32 v174, v106, v174
	v_mul_f32_e32 v175, v107, v175
	v_mul_f32_e32 v176, v96, v176
	v_mul_f32_e32 v177, v97, v177
	v_mul_f32_e32 v178, v98, v178
	v_mul_f32_e32 v179, v99, v179
	v_mul_f32_e32 v104, v108, v172
	v_mul_f32_e32 v105, v109, v173
	v_mul_f32_e32 v106, v110, v174
	v_mul_f32_e32 v107, v111, v175
	v_mul_f32_e32 v96, v100, v176
	v_mul_f32_e32 v97, v101, v177
	v_mul_f32_e32 v98, v102, v178
	v_mul_f32_e32 v99, v103, v179
	v_cvt_pk_bf16_f32 v180, v104, v105
	v_cvt_pk_bf16_f32 v181, v106, v107
	v_cvt_pk_bf16_f32 v182, v96, v97
	v_cvt_pk_bf16_f32 v183, v98, v99
	v_mov_b32_dpp v184, v180 quad_perm:[1,0,3,2] row_mask:0xf bank_mask:0xf bound_ctrl:1
	v_mov_b32_dpp v185, v181 quad_perm:[1,0,3,2] row_mask:0xf bank_mask:0xf bound_ctrl:1
	v_mov_b32_dpp v186, v182 quad_perm:[1,0,3,2] row_mask:0xf bank_mask:0xf bound_ctrl:1
	v_mov_b32_dpp v187, v183 quad_perm:[1,0,3,2] row_mask:0xf bank_mask:0xf bound_ctrl:1
	v_perm_b32 v180, v184, v180, v164
	v_perm_b32 v181, v185, v181, v164
	v_perm_b32 v182, v186, v182, v164
	v_perm_b32 v183, v187, v183, v164
	global_store_dword v169, v180, s[34:35]
	global_store_dword v170, v181, s[34:35]
	global_store_dword v169, v182, s[34:35] offset:32
	global_store_dword v170, v183, s[34:35] offset:32
	v_add_u32_e32 v169, 0x2c000, v166
	v_add_u32_e32 v170, 0x2ec00, v166
	v_mul_f32_e32 v88, v88, v138
	v_mul_f32_e32 v89, v89, v139
	v_mul_f32_e32 v90, v90, v140
	v_mul_f32_e32 v91, v91, v141
	v_mul_f32_e32 v80, v80, v138
	v_mul_f32_e32 v81, v81, v139
	v_mul_f32_e32 v82, v82, v140
	v_mul_f32_e32 v83, v83, v141
	v_mul_f32_e32 v92, v92, v138
	v_mul_f32_e32 v93, v93, v139
	v_mul_f32_e32 v94, v94, v140
	v_mul_f32_e32 v95, v95, v141
	v_mul_f32_e32 v84, v84, v138
	v_mul_f32_e32 v85, v85, v139
	v_mul_f32_e32 v86, v86, v140
	v_mul_f32_e32 v87, v87, v141
	v_mul_f32_e32 v172, 0xbfb8aa3b, v88
	v_mul_f32_e32 v173, 0xbfb8aa3b, v89
	v_mul_f32_e32 v174, 0xbfb8aa3b, v90
	v_mul_f32_e32 v175, 0xbfb8aa3b, v91
	v_mul_f32_e32 v176, 0xbfb8aa3b, v80
	v_mul_f32_e32 v177, 0xbfb8aa3b, v81
	v_mul_f32_e32 v178, 0xbfb8aa3b, v82
	v_mul_f32_e32 v179, 0xbfb8aa3b, v83
	v_exp_f32_e32 v172, v172
	v_exp_f32_e32 v173, v173
	v_exp_f32_e32 v174, v174
	v_exp_f32_e32 v175, v175
	v_exp_f32_e32 v176, v176
	v_exp_f32_e32 v177, v177
	v_exp_f32_e32 v178, v178
	v_exp_f32_e32 v179, v179
	v_add_f32_e32 v172, 1.0, v172
	v_add_f32_e32 v173, 1.0, v173
	v_add_f32_e32 v174, 1.0, v174
	v_add_f32_e32 v175, 1.0, v175
	v_add_f32_e32 v176, 1.0, v176
	v_add_f32_e32 v177, 1.0, v177
	v_add_f32_e32 v178, 1.0, v178
	v_add_f32_e32 v179, 1.0, v179
	v_rcp_f32_e32 v172, v172
	v_rcp_f32_e32 v173, v173
	v_rcp_f32_e32 v174, v174
	v_rcp_f32_e32 v175, v175
	v_rcp_f32_e32 v176, v176
	v_rcp_f32_e32 v177, v177
	v_rcp_f32_e32 v178, v178
	v_rcp_f32_e32 v179, v179
	v_mul_f32_e32 v172, v88, v172
	v_mul_f32_e32 v173, v89, v173
	v_mul_f32_e32 v174, v90, v174
	v_mul_f32_e32 v175, v91, v175
	v_mul_f32_e32 v176, v80, v176
	v_mul_f32_e32 v177, v81, v177
	v_mul_f32_e32 v178, v82, v178
	v_mul_f32_e32 v179, v83, v179
	v_mul_f32_e32 v88, v92, v172
; __device__ __forceinline__ float fast_silu(float z) { return z * __builtin_amdgcn_rcpf(1.f + __expf(-z)); }
; __device__ __forceinline__ void store_rm4(u16* dst, size_t ld, int row0, int c, float v0, float v1, float v2, float v3, bool odd) {
;   {
;     float s = odd ? v0 : v1, r = dpp_swap1(s);
;     float lo = odd ? r : v0, hi = odd ? v1 : r;
;     *(unsigned*)(dst + (size_t)(row0 + (odd ? 1 : 0)) * ld + (c - (odd ? 1 : 0))) = pack2(lo, hi);
;   }
;   {
;     float s = odd ? v2 : v3, r = dpp_swap1(s);
;     float lo = odd ? r : v2, hi = odd ? v3 : r;
;     *(unsigned*)(dst + (size_t)(row0 + 2 + (odd ? 1 : 0)) * ld + (c - (odd ? 1 : 0))) = pack2(lo, hi);
;   }
; }
;   __device__ __forceinline__ void operator()(f32x4 (&acc)[2][2][4][2], int brow, int bcol, int wr, int wc, int fr, int fq) const {
;     ...
; #pragma unroll
;         for (int n = 0; n < 2; ++n) {
;           float a[4];
; #pragma unroll
;           for (int j = 0; j < 4; ++j) {
;             float g = acc[ai][0][m][n][j] * rs[j], u = acc[ai][1][m][n][j] * rs[j];
;             a[j] = fast_silu(g) * u;
;           }
;           store_rm4(act, 2816, row0, t * 128 + wc * 32 + n * 16 + fr, a[0], a[1], a[2], a[3], fr & 1);
;         }
	v_mul_f32_e32 v89, v93, v173
	v_mul_f32_e32 v90, v94, v174
	v_mul_f32_e32 v91, v95, v175
	v_mul_f32_e32 v80, v84, v176
	v_mul_f32_e32 v81, v85, v177
	v_mul_f32_e32 v82, v86, v178
	v_mul_f32_e32 v83, v87, v179
	v_cvt_pk_bf16_f32 v180, v88, v89
	v_cvt_pk_bf16_f32 v181, v90, v91
	v_cvt_pk_bf16_f32 v182, v80, v81
	v_cvt_pk_bf16_f32 v183, v82, v83
	v_mov_b32_dpp v184, v180 quad_perm:[1,0,3,2] row_mask:0xf bank_mask:0xf bound_ctrl:1
	v_mov_b32_dpp v185, v181 quad_perm:[1,0,3,2] row_mask:0xf bank_mask:0xf bound_ctrl:1
	v_mov_b32_dpp v186, v182 quad_perm:[1,0,3,2] row_mask:0xf bank_mask:0xf bound_ctrl:1
	v_mov_b32_dpp v187, v183 quad_perm:[1,0,3,2] row_mask:0xf bank_mask:0xf bound_ctrl:1
	v_perm_b32 v180, v184, v180, v164
	v_perm_b32 v181, v185, v181, v164
	v_perm_b32 v182, v186, v182, v164
	v_perm_b32 v183, v187, v183, v164
	global_store_dword v169, v180, s[34:35]
	global_store_dword v170, v181, s[34:35]
	global_store_dword v169, v182, s[34:35] offset:32
	global_store_dword v170, v183, s[34:35] offset:32
	v_add_u32_e32 v169, 0x42000, v166
	v_add_u32_e32 v170, 0x44c00, v166
	v_mul_f32_e32 v72, v72, v142
	v_mul_f32_e32 v73, v73, v143
	v_mul_f32_e32 v74, v74, v144
	v_mul_f32_e32 v75, v75, v145
	v_mul_f32_e32 v64, v64, v142
	v_mul_f32_e32 v65, v65, v143
	v_mul_f32_e32 v66, v66, v144
	v_mul_f32_e32 v67, v67, v145
	v_mul_f32_e32 v76, v76, v142
	v_mul_f32_e32 v77, v77, v143
	v_mul_f32_e32 v78, v78, v144
	v_mul_f32_e32 v79, v79, v145
	v_mul_f32_e32 v68, v68, v142
	v_mul_f32_e32 v69, v69, v143
	v_mul_f32_e32 v70, v70, v144
	v_mul_f32_e32 v71, v71, v145
	v_mul_f32_e32 v172, 0xbfb8aa3b, v72
	v_mul_f32_e32 v173, 0xbfb8aa3b, v73
	v_mul_f32_e32 v174, 0xbfb8aa3b, v74
	v_mul_f32_e32 v175, 0xbfb8aa3b, v75
	v_mul_f32_e32 v176, 0xbfb8aa3b, v64
	v_mul_f32_e32 v177, 0xbfb8aa3b, v65
	v_mul_f32_e32 v178, 0xbfb8aa3b, v66
	v_mul_f32_e32 v179, 0xbfb8aa3b, v67
	v_exp_f32_e32 v172, v172
	v_exp_f32_e32 v173, v173
	v_exp_f32_e32 v174, v174
	v_exp_f32_e32 v175, v175
	v_exp_f32_e32 v176, v176
	v_exp_f32_e32 v177, v177
	v_exp_f32_e32 v178, v178
	v_exp_f32_e32 v179, v179
	v_add_f32_e32 v172, 1.0, v172
	v_add_f32_e32 v173, 1.0, v173
	v_add_f32_e32 v174, 1.0, v174
	v_add_f32_e32 v175, 1.0, v175
	v_add_f32_e32 v176, 1.0, v176
	v_add_f32_e32 v177, 1.0, v177
	v_add_f32_e32 v178, 1.0, v178
	v_add_f32_e32 v179, 1.0, v179
	v_rcp_f32_e32 v172, v172
	v_rcp_f32_e32 v173, v173
	v_rcp_f32_e32 v174, v174
	v_rcp_f32_e32 v175, v175
	v_rcp_f32_e32 v176, v176
	v_rcp_f32_e32 v177, v177
	v_rcp_f32_e32 v178, v178
	v_rcp_f32_e32 v179, v179
	v_mul_f32_e32 v172, v72, v172
	v_mul_f32_e32 v173, v73, v173
	v_mul_f32_e32 v174, v74, v174
	v_mul_f32_e32 v175, v75, v175
	v_mul_f32_e32 v176, v64, v176
	v_mul_f32_e32 v177, v65, v177
	v_mul_f32_e32 v178, v66, v178
	v_mul_f32_e32 v179, v67, v179
	v_mul_f32_e32 v72, v76, v172
	v_mul_f32_e32 v73, v77, v173
	v_mul_f32_e32 v74, v78, v174
	v_mul_f32_e32 v75, v79, v175
	v_mul_f32_e32 v64, v68, v176
	v_mul_f32_e32 v65, v69, v177
	v_mul_f32_e32 v66, v70, v178
	v_mul_f32_e32 v67, v71, v179
	v_cvt_pk_bf16_f32 v180, v72, v73
	v_cvt_pk_bf16_f32 v181, v74, v75
	v_cvt_pk_bf16_f32 v182, v64, v65
	v_cvt_pk_bf16_f32 v183, v66, v67
	v_mov_b32_dpp v184, v180 quad_perm:[1,0,3,2] row_mask:0xf bank_mask:0xf bound_ctrl:1
	v_mov_b32_dpp v185, v181 quad_perm:[1,0,3,2] row_mask:0xf bank_mask:0xf bound_ctrl:1
	v_mov_b32_dpp v186, v182 quad_perm:[1,0,3,2] row_mask:0xf bank_mask:0xf bound_ctrl:1
	v_mov_b32_dpp v187, v183 quad_perm:[1,0,3,2] row_mask:0xf bank_mask:0xf bound_ctrl:1
	v_perm_b32 v180, v184, v180, v164
	v_perm_b32 v181, v185, v181, v164
	v_perm_b32 v182, v186, v182, v164
	v_perm_b32 v183, v187, v183, v164
	global_store_dword v169, v180, s[34:35]
	global_store_dword v170, v181, s[34:35]
	global_store_dword v169, v182, s[34:35] offset:32
	global_store_dword v170, v183, s[34:35] offset:32
	v_add_u32_e32 v169, 0xb0000, v166
	v_add_u32_e32 v170, 0xb2c00, v166
	v_mul_f32_e32 v56, v56, v146
	v_mul_f32_e32 v57, v57, v147
	v_mul_f32_e32 v58, v58, v148
	v_mul_f32_e32 v59, v59, v149
	v_mul_f32_e32 v48, v48, v146
	v_mul_f32_e32 v49, v49, v147
	v_mul_f32_e32 v50, v50, v148
	v_mul_f32_e32 v51, v51, v149
	v_mul_f32_e32 v60, v60, v146
	v_mul_f32_e32 v61, v61, v147
	v_mul_f32_e32 v62, v62, v148
	v_mul_f32_e32 v63, v63, v149
	v_mul_f32_e32 v52, v52, v146
	v_mul_f32_e32 v53, v53, v147
	v_mul_f32_e32 v54, v54, v148
	v_mul_f32_e32 v55, v55, v149
	v_mul_f32_e32 v172, 0xbfb8aa3b, v56
	v_mul_f32_e32 v173, 0xbfb8aa3b, v57
	v_mul_f32_e32 v174, 0xbfb8aa3b, v58
	v_mul_f32_e32 v175, 0xbfb8aa3b, v59
	v_mul_f32_e32 v176, 0xbfb8aa3b, v48
	v_mul_f32_e32 v177, 0xbfb8aa3b, v49
	v_mul_f32_e32 v178, 0xbfb8aa3b, v50
	v_mul_f32_e32 v179, 0xbfb8aa3b, v51
	v_exp_f32_e32 v172, v172
	v_exp_f32_e32 v173, v173
	v_exp_f32_e32 v174, v174
	v_exp_f32_e32 v175, v175
	v_exp_f32_e32 v176, v176
	v_exp_f32_e32 v177, v177
	v_exp_f32_e32 v178, v178
	v_exp_f32_e32 v179, v179
	v_add_f32_e32 v172, 1.0, v172
	v_add_f32_e32 v173, 1.0, v173
	v_add_f32_e32 v174, 1.0, v174
	v_add_f32_e32 v175, 1.0, v175
	v_add_f32_e32 v176, 1.0, v176
	v_add_f32_e32 v177, 1.0, v177
	v_add_f32_e32 v178, 1.0, v178
	v_add_f32_e32 v179, 1.0, v179
	v_rcp_f32_e32 v172, v172
	v_rcp_f32_e32 v173, v173
	v_rcp_f32_e32 v174, v174
	v_rcp_f32_e32 v175, v175
	v_rcp_f32_e32 v176, v176
	v_rcp_f32_e32 v177, v177
	v_rcp_f32_e32 v178, v178
	v_rcp_f32_e32 v179, v179
	v_mul_f32_e32 v172, v56, v172
	v_mul_f32_e32 v173, v57, v173
	v_mul_f32_e32 v174, v58, v174
	v_mul_f32_e32 v175, v59, v175
	v_mul_f32_e32 v176, v48, v176
	v_mul_f32_e32 v177, v49, v177
	v_mul_f32_e32 v178, v50, v178
	v_mul_f32_e32 v179, v51, v179
	v_mul_f32_e32 v56, v60, v172
	v_mul_f32_e32 v57, v61, v173
; __device__ __forceinline__ float fast_silu(float z) { return z * __builtin_amdgcn_rcpf(1.f + __expf(-z)); }
; __device__ __forceinline__ void store_rm4(u16* dst, size_t ld, int row0, int c, float v0, float v1, float v2, float v3, bool odd) {
;   {
;     float s = odd ? v0 : v1, r = dpp_swap1(s);
;     float lo = odd ? r : v0, hi = odd ? v1 : r;
;     *(unsigned*)(dst + (size_t)(row0 + (odd ? 1 : 0)) * ld + (c - (odd ? 1 : 0))) = pack2(lo, hi);
;   }
;   {
;     float s = odd ? v2 : v3, r = dpp_swap1(s);
;     float lo = odd ? r : v2, hi = odd ? v3 : r;
;     *(unsigned*)(dst + (size_t)(row0 + 2 + (odd ? 1 : 0)) * ld + (c - (odd ? 1 : 0))) = pack2(lo, hi);
;   }
; }
;   __device__ __forceinline__ void operator()(f32x4 (&acc)[2][2][4][2], int brow, int bcol, int wr, int wc, int fr, int fq) const {
;     ...
; #pragma unroll
;         for (int n = 0; n < 2; ++n) {
;           float a[4];
; #pragma unroll
;           for (int j = 0; j < 4; ++j) {
;             float g = acc[ai][0][m][n][j] * rs[j], u = acc[ai][1][m][n][j] * rs[j];
;             a[j] = fast_silu(g) * u;
;           }
;           store_rm4(act, 2816, row0, t * 128 + wc * 32 + n * 16 + fr, a[0], a[1], a[2], a[3], fr & 1);
;         }
	v_mul_f32_e32 v58, v62, v174
	v_mul_f32_e32 v59, v63, v175
	v_mul_f32_e32 v48, v52, v176
	v_mul_f32_e32 v49, v53, v177
	v_mul_f32_e32 v50, v54, v178
	v_mul_f32_e32 v51, v55, v179
	v_cvt_pk_bf16_f32 v180, v56, v57
	v_cvt_pk_bf16_f32 v181, v58, v59
	v_cvt_pk_bf16_f32 v182, v48, v49
	v_cvt_pk_bf16_f32 v183, v50, v51
	v_mov_b32_dpp v184, v180 quad_perm:[1,0,3,2] row_mask:0xf bank_mask:0xf bound_ctrl:1
	v_mov_b32_dpp v185, v181 quad_perm:[1,0,3,2] row_mask:0xf bank_mask:0xf bound_ctrl:1
	v_mov_b32_dpp v186, v182 quad_perm:[1,0,3,2] row_mask:0xf bank_mask:0xf bound_ctrl:1
	v_mov_b32_dpp v187, v183 quad_perm:[1,0,3,2] row_mask:0xf bank_mask:0xf bound_ctrl:1
	v_perm_b32 v180, v184, v180, v164
	v_perm_b32 v181, v185, v181, v164
	v_perm_b32 v182, v186, v182, v164
	v_perm_b32 v183, v187, v183, v164
	global_store_dword v169, v180, s[34:35]
	global_store_dword v170, v181, s[34:35]
	global_store_dword v169, v182, s[34:35] offset:32
	global_store_dword v170, v183, s[34:35] offset:32
	v_add_u32_e32 v169, 0xc6000, v166
	v_add_u32_e32 v170, 0xc8c00, v166
	v_mul_f32_e32 v40, v40, v150
	v_mul_f32_e32 v41, v41, v151
	v_mul_f32_e32 v42, v42, v152
	v_mul_f32_e32 v43, v43, v153
	v_mul_f32_e32 v32, v32, v150
	v_mul_f32_e32 v33, v33, v151
	v_mul_f32_e32 v34, v34, v152
	v_mul_f32_e32 v35, v35, v153
	v_mul_f32_e32 v44, v44, v150
	v_mul_f32_e32 v45, v45, v151
	v_mul_f32_e32 v46, v46, v152
	v_mul_f32_e32 v47, v47, v153
	v_mul_f32_e32 v36, v36, v150
	v_mul_f32_e32 v37, v37, v151
	v_mul_f32_e32 v38, v38, v152
	v_mul_f32_e32 v39, v39, v153
	v_mul_f32_e32 v172, 0xbfb8aa3b, v40
	v_mul_f32_e32 v173, 0xbfb8aa3b, v41
	v_mul_f32_e32 v174, 0xbfb8aa3b, v42
	v_mul_f32_e32 v175, 0xbfb8aa3b, v43
	v_mul_f32_e32 v176, 0xbfb8aa3b, v32
	v_mul_f32_e32 v177, 0xbfb8aa3b, v33
	v_mul_f32_e32 v178, 0xbfb8aa3b, v34
	v_mul_f32_e32 v179, 0xbfb8aa3b, v35
	v_exp_f32_e32 v172, v172
	v_exp_f32_e32 v173, v173
	v_exp_f32_e32 v174, v174
	v_exp_f32_e32 v175, v175
	v_exp_f32_e32 v176, v176
	v_exp_f32_e32 v177, v177
	v_exp_f32_e32 v178, v178
	v_exp_f32_e32 v179, v179
	v_add_f32_e32 v172, 1.0, v172
	v_add_f32_e32 v173, 1.0, v173
	v_add_f32_e32 v174, 1.0, v174
	v_add_f32_e32 v175, 1.0, v175
	v_add_f32_e32 v176, 1.0, v176
	v_add_f32_e32 v177, 1.0, v177
	v_add_f32_e32 v178, 1.0, v178
	v_add_f32_e32 v179, 1.0, v179
	v_rcp_f32_e32 v172, v172
	v_rcp_f32_e32 v173, v173
	v_rcp_f32_e32 v174, v174
	v_rcp_f32_e32 v175, v175
	v_rcp_f32_e32 v176, v176
	v_rcp_f32_e32 v177, v177
	v_rcp_f32_e32 v178, v178
	v_rcp_f32_e32 v179, v179
	v_mul_f32_e32 v172, v40, v172
	v_mul_f32_e32 v173, v41, v173
	v_mul_f32_e32 v174, v42, v174
	v_mul_f32_e32 v175, v43, v175
	v_mul_f32_e32 v176, v32, v176
	v_mul_f32_e32 v177, v33, v177
	v_mul_f32_e32 v178, v34, v178
	v_mul_f32_e32 v179, v35, v179
	v_mul_f32_e32 v40, v44, v172
	v_mul_f32_e32 v41, v45, v173
	v_mul_f32_e32 v42, v46, v174
	v_mul_f32_e32 v43, v47, v175
	v_mul_f32_e32 v32, v36, v176
	v_mul_f32_e32 v33, v37, v177
	v_mul_f32_e32 v34, v38, v178
	v_mul_f32_e32 v35, v39, v179
	v_cvt_pk_bf16_f32 v180, v40, v41
	v_cvt_pk_bf16_f32 v181, v42, v43
	v_cvt_pk_bf16_f32 v182, v32, v33
	v_cvt_pk_bf16_f32 v183, v34, v35
	v_mov_b32_dpp v184, v180 quad_perm:[1,0,3,2] row_mask:0xf bank_mask:0xf bound_ctrl:1
	v_mov_b32_dpp v185, v181 quad_perm:[1,0,3,2] row_mask:0xf bank_mask:0xf bound_ctrl:1
	v_mov_b32_dpp v186, v182 quad_perm:[1,0,3,2] row_mask:0xf bank_mask:0xf bound_ctrl:1
	v_mov_b32_dpp v187, v183 quad_perm:[1,0,3,2] row_mask:0xf bank_mask:0xf bound_ctrl:1
	v_perm_b32 v180, v184, v180, v164
	v_perm_b32 v181, v185, v181, v164
	v_perm_b32 v182, v186, v182, v164
	v_perm_b32 v183, v187, v183, v164
	global_store_dword v169, v180, s[34:35]
	global_store_dword v170, v181, s[34:35]
	global_store_dword v169, v182, s[34:35] offset:32
	global_store_dword v170, v183, s[34:35] offset:32
	v_add_u32_e32 v169, 0xdc000, v166
	v_add_u32_e32 v170, 0xdec00, v166
	v_mul_f32_e32 v24, v24, v154
	v_mul_f32_e32 v25, v25, v155
	v_mul_f32_e32 v26, v26, v156
	v_mul_f32_e32 v27, v27, v157
	v_mul_f32_e32 v16, v16, v154
	v_mul_f32_e32 v17, v17, v155
	v_mul_f32_e32 v18, v18, v156
	v_mul_f32_e32 v19, v19, v157
	v_mul_f32_e32 v28, v28, v154
	v_mul_f32_e32 v29, v29, v155
	v_mul_f32_e32 v30, v30, v156
	v_mul_f32_e32 v31, v31, v157
	v_mul_f32_e32 v20, v20, v154
	v_mul_f32_e32 v21, v21, v155
	v_mul_f32_e32 v22, v22, v156
	v_mul_f32_e32 v23, v23, v157
	v_mul_f32_e32 v172, 0xbfb8aa3b, v24
	v_mul_f32_e32 v173, 0xbfb8aa3b, v25
	v_mul_f32_e32 v174, 0xbfb8aa3b, v26
	v_mul_f32_e32 v175, 0xbfb8aa3b, v27
	v_mul_f32_e32 v176, 0xbfb8aa3b, v16
	v_mul_f32_e32 v177, 0xbfb8aa3b, v17
	v_mul_f32_e32 v178, 0xbfb8aa3b, v18
	v_mul_f32_e32 v179, 0xbfb8aa3b, v19
	v_exp_f32_e32 v172, v172
	v_exp_f32_e32 v173, v173
	v_exp_f32_e32 v174, v174
	v_exp_f32_e32 v175, v175
; __device__ __forceinline__ float fast_silu(float z) { return z * __builtin_amdgcn_rcpf(1.f + __expf(-z)); }
; #define WAIT_L(n) asm volatile("s_waitcnt lgkmcnt(" #n ")" ::: "memory")
; #define BAR __builtin_amdgcn_s_barrier()
; template <class Epi>
; __device__ __forceinline__ void gemm_tile(const u16* __restrict__ A, const u16* __restrict__ Bt, int K,
;                                           int brow, int bcol, bool first, bool has_next, int nbrow, int nbcol, Epi epi) {
;     ...
;   WAIT_L(0); BAR;
;   __device__ __forceinline__ void operator()(f32x4 (&acc)[2][2][4][2], int brow, int bcol, int wr, int wc, int fr, int fq) const {
;     ...
; #pragma unroll
;         for (int n = 0; n < 2; ++n) {
;           float a[4];
; #pragma unroll
;           for (int j = 0; j < 4; ++j) {
;             float g = acc[ai][0][m][n][j] * rs[j], u = acc[ai][1][m][n][j] * rs[j];
;             a[j] = fast_silu(g) * u;
;           }
;           store_rm4(act, 2816, row0, t * 128 + wc * 32 + n * 16 + fr, a[0], a[1], a[2], a[3], fr & 1);
;         }
	v_exp_f32_e32 v176, v176
	v_exp_f32_e32 v177, v177
	v_exp_f32_e32 v178, v178
	v_exp_f32_e32 v179, v179
	v_add_f32_e32 v172, 1.0, v172
	v_add_f32_e32 v173, 1.0, v173
	v_add_f32_e32 v174, 1.0, v174
	v_add_f32_e32 v175, 1.0, v175
	v_add_f32_e32 v176, 1.0, v176
	v_add_f32_e32 v177, 1.0, v177
	v_add_f32_e32 v178, 1.0, v178
	v_add_f32_e32 v179, 1.0, v179
	v_rcp_f32_e32 v172, v172
	v_rcp_f32_e32 v173, v173
	v_rcp_f32_e32 v174, v174
	v_rcp_f32_e32 v175, v175
	v_rcp_f32_e32 v176, v176
	v_rcp_f32_e32 v177, v177
	v_rcp_f32_e32 v178, v178
	v_rcp_f32_e32 v179, v179
	v_mul_f32_e32 v172, v24, v172
	v_mul_f32_e32 v173, v25, v173
	v_mul_f32_e32 v174, v26, v174
	v_mul_f32_e32 v175, v27, v175
	v_mul_f32_e32 v176, v16, v176
	v_mul_f32_e32 v177, v17, v177
	v_mul_f32_e32 v178, v18, v178
	v_mul_f32_e32 v179, v19, v179
	v_mul_f32_e32 v24, v28, v172
	v_mul_f32_e32 v25, v29, v173
	v_mul_f32_e32 v26, v30, v174
	v_mul_f32_e32 v27, v31, v175
	v_mul_f32_e32 v16, v20, v176
	v_mul_f32_e32 v17, v21, v177
	v_mul_f32_e32 v18, v22, v178
	v_mul_f32_e32 v19, v23, v179
	v_cvt_pk_bf16_f32 v180, v24, v25
	v_cvt_pk_bf16_f32 v181, v26, v27
	v_cvt_pk_bf16_f32 v182, v16, v17
	v_cvt_pk_bf16_f32 v183, v18, v19
	v_mov_b32_dpp v184, v180 quad_perm:[1,0,3,2] row_mask:0xf bank_mask:0xf bound_ctrl:1
	v_mov_b32_dpp v185, v181 quad_perm:[1,0,3,2] row_mask:0xf bank_mask:0xf bound_ctrl:1
	v_mov_b32_dpp v186, v182 quad_perm:[1,0,3,2] row_mask:0xf bank_mask:0xf bound_ctrl:1
	v_mov_b32_dpp v187, v183 quad_perm:[1,0,3,2] row_mask:0xf bank_mask:0xf bound_ctrl:1
	v_perm_b32 v180, v184, v180, v164
	v_perm_b32 v181, v185, v181, v164
	v_perm_b32 v182, v186, v182, v164
	v_perm_b32 v183, v187, v183, v164
	global_store_dword v169, v180, s[34:35]
	global_store_dword v170, v181, s[34:35]
	global_store_dword v169, v182, s[34:35] offset:32
	global_store_dword v170, v183, s[34:35] offset:32
	v_add_u32_e32 v169, 0xf2000, v166
	v_add_u32_e32 v170, 0xf4c00, v166
	v_mul_f32_e32 v8, v8, v158
	v_mul_f32_e32 v9, v9, v159
	v_mul_f32_e32 v10, v10, v160
	v_mul_f32_e32 v11, v11, v161
	v_mul_f32_e32 v0, v0, v158
	v_mul_f32_e32 v1, v1, v159
	v_mul_f32_e32 v2, v2, v160
	v_mul_f32_e32 v3, v3, v161
	v_mul_f32_e32 v12, v12, v158
	v_mul_f32_e32 v13, v13, v159
	v_mul_f32_e32 v14, v14, v160
	v_mul_f32_e32 v15, v15, v161
	v_mul_f32_e32 v4, v4, v158
	v_mul_f32_e32 v5, v5, v159
	v_mul_f32_e32 v6, v6, v160
	v_mul_f32_e32 v7, v7, v161
	v_mul_f32_e32 v172, 0xbfb8aa3b, v8
	v_mul_f32_e32 v173, 0xbfb8aa3b, v9
	v_mul_f32_e32 v174, 0xbfb8aa3b, v10
	v_mul_f32_e32 v175, 0xbfb8aa3b, v11
	v_mul_f32_e32 v176, 0xbfb8aa3b, v0
	v_mul_f32_e32 v177, 0xbfb8aa3b, v1
	v_mul_f32_e32 v178, 0xbfb8aa3b, v2
	v_mul_f32_e32 v179, 0xbfb8aa3b, v3
	v_exp_f32_e32 v172, v172
	v_exp_f32_e32 v173, v173
	v_exp_f32_e32 v174, v174
	v_exp_f32_e32 v175, v175
	v_exp_f32_e32 v176, v176
	v_exp_f32_e32 v177, v177
	v_exp_f32_e32 v178, v178
	v_exp_f32_e32 v179, v179
	v_add_f32_e32 v172, 1.0, v172
	v_add_f32_e32 v173, 1.0, v173
	v_add_f32_e32 v174, 1.0, v174
	v_add_f32_e32 v175, 1.0, v175
	v_add_f32_e32 v176, 1.0, v176
	v_add_f32_e32 v177, 1.0, v177
	v_add_f32_e32 v178, 1.0, v178
	v_add_f32_e32 v179, 1.0, v179
	v_rcp_f32_e32 v172, v172
	v_rcp_f32_e32 v173, v173
	v_rcp_f32_e32 v174, v174
	v_rcp_f32_e32 v175, v175
	v_rcp_f32_e32 v176, v176
	v_rcp_f32_e32 v177, v177
	v_rcp_f32_e32 v178, v178
	v_rcp_f32_e32 v179, v179
	v_mul_f32_e32 v172, v8, v172
	v_mul_f32_e32 v173, v9, v173
	v_mul_f32_e32 v174, v10, v174
	v_mul_f32_e32 v175, v11, v175
	v_mul_f32_e32 v176, v0, v176
	v_mul_f32_e32 v177, v1, v177
	v_mul_f32_e32 v178, v2, v178
	v_mul_f32_e32 v179, v3, v179
	v_mul_f32_e32 v8, v12, v172
	v_mul_f32_e32 v9, v13, v173
	v_mul_f32_e32 v10, v14, v174
	v_mul_f32_e32 v11, v15, v175
	v_mul_f32_e32 v0, v4, v176
	v_mul_f32_e32 v1, v5, v177
	v_mul_f32_e32 v2, v6, v178
	v_mul_f32_e32 v3, v7, v179
	v_cvt_pk_bf16_f32 v180, v8, v9
	v_cvt_pk_bf16_f32 v181, v10, v11
	v_cvt_pk_bf16_f32 v182, v0, v1
	v_cvt_pk_bf16_f32 v183, v2, v3
	v_mov_b32_dpp v184, v180 quad_perm:[1,0,3,2] row_mask:0xf bank_mask:0xf bound_ctrl:1
	v_mov_b32_dpp v185, v181 quad_perm:[1,0,3,2] row_mask:0xf bank_mask:0xf bound_ctrl:1
	v_mov_b32_dpp v186, v182 quad_perm:[1,0,3,2] row_mask:0xf bank_mask:0xf bound_ctrl:1
	v_mov_b32_dpp v187, v183 quad_perm:[1,0,3,2] row_mask:0xf bank_mask:0xf bound_ctrl:1
	v_perm_b32 v180, v184, v180, v164
	v_perm_b32 v181, v185, v181, v164
	v_perm_b32 v182, v186, v182, v164
	v_perm_b32 v183, v187, v183, v164
	global_store_dword v169, v180, s[34:35]
	global_store_dword v170, v181, s[34:35]
	global_store_dword v169, v182, s[34:35] offset:32
	global_store_dword v170, v183, s[34:35] offset:32
	s_waitcnt lgkmcnt(0)
	s_cmp_lg_u32 s64, 22
	s_mov_b32 s2, s30
	s_mov_b32 s0, s28
	s_mov_b32 s1, s64
	s_barrier
	s_cbranch_scc0 .LBB0_597

; __global__ void __launch_bounds__(512) fwd_mega(P pin) {
;   cg::grid_group grid = cg::this_grid();
;   P p = pin; p.wv = __builtin_amdgcn_readfirstlane((int)(threadIdx.x >> 6));
	.amdhsa_kernel _Z8fwd_mega1P
		.amdhsa_group_segment_fixed_size 16
		.amdhsa_private_segment_fixed_size 0
		.amdhsa_kernarg_size 408
		.amdhsa_user_sgpr_count 2
		.amdhsa_user_sgpr_dispatch_ptr 0
		.amdhsa_user_sgpr_queue_ptr 0
		.amdhsa_user_sgpr_kernarg_segment_ptr 1
		.amdhsa_user_sgpr_dispatch_id 0
		.amdhsa_user_sgpr_kernarg_preload_length 0
		.amdhsa_user_sgpr_kernarg_preload_offset 0
		.amdhsa_user_sgpr_private_segment_size 0
		.amdhsa_uses_dynamic_stack 0
		.amdhsa_enable_private_segment 0
		.amdhsa_system_sgpr_workgroup_id_x 1
		.amdhsa_system_sgpr_workgroup_id_y 0
		.amdhsa_system_sgpr_workgroup_id_z 0
		.amdhsa_system_sgpr_workgroup_info 0
		.amdhsa_system_vgpr_workitem_id 2
		.amdhsa_next_free_vgpr 256
		.amdhsa_next_free_sgpr 102
		.amdhsa_accum_offset 256
		.amdhsa_reserve_vcc 1
		.amdhsa_float_round_mode_32 0
		.amdhsa_float_round_mode_16_64 0
		.amdhsa_float_denorm_mode_32 3
		.amdhsa_float_denorm_mode_16_64 3
		.amdhsa_dx10_clamp 1
		.amdhsa_ieee_mode 1
		.amdhsa_fp16_overflow 0
		.amdhsa_tg_split 0
		.amdhsa_exception_fp_ieee_invalid_op 0
		.amdhsa_exception_fp_denorm_src 0
		.amdhsa_exception_fp_ieee_div_zero 0
		.amdhsa_exception_fp_ieee_overflow 0
		.amdhsa_exception_fp_ieee_underflow 0
		.amdhsa_exception_fp_ieee_inexact 0
		.amdhsa_exception_int_div_zero 0
	.end_amdhsa_kernel

; __global__ void __launch_bounds__(512) fwd_mega(P pin) {
;   cg::grid_group grid = cg::this_grid();
;   P p = pin; p.wv = __builtin_amdgcn_readfirstlane((int)(threadIdx.x >> 6));
amdhsa.kernels:
  - .agpr_count:     0
    .args:
      - .offset:         0
        .size:           152
        .value_kind:     by_value
      - .offset:         152
        .size:           4
        .value_kind:     hidden_block_count_x
      - .offset:         156
        .size:           4
        .value_kind:     hidden_block_count_y
      - .offset:         160
        .size:           4
        .value_kind:     hidden_block_count_z
      - .offset:         164
        .size:           2
        .value_kind:     hidden_group_size_x
      - .offset:         166
        .size:           2
        .value_kind:     hidden_group_size_y
      - .offset:         168
        .size:           2
        .value_kind:     hidden_group_size_z
      - .offset:         170
        .size:           2
        .value_kind:     hidden_remainder_x
      - .offset:         172
        .size:           2
        .value_kind:     hidden_remainder_y
      - .offset:         174
        .size:           2
        .value_kind:     hidden_remainder_z
      - .offset:         192
        .size:           8
        .value_kind:     hidden_global_offset_x
      - .offset:         200
        .size:           8
        .value_kind:     hidden_global_offset_y
      - .offset:         208
        .size:           8
        .value_kind:     hidden_global_offset_z
      - .offset:         216
        .size:           2
        .value_kind:     hidden_grid_dims
      - .offset:         240
        .size:           8
        .value_kind:     hidden_multigrid_sync_arg
      - .offset:         272
        .size:           4
        .value_kind:     hidden_dynamic_lds_size
    .group_segment_fixed_size: 16
    .kernarg_segment_align: 8
    .kernarg_segment_size: 408
    .language:       OpenCL C
    .language_version:
      - 2
      - 0
    .max_flat_workgroup_size: 512
    .name:           _Z8fwd_mega1P
    .private_segment_fixed_size: 0
    .sgpr_count:     108
    .sgpr_spill_count: 3
    .symbol:         _Z8fwd_mega1P.kd
    .uniform_work_group_size: 1
    .uses_dynamic_stack: false
    .vgpr_count:     256
    .vgpr_spill_count: 0
    .wavefront_size: 64
